# hgrn_pass2 RMS-norm lane reductions (xor 1/2/4/8) as DPP moves (quad_perm, row_half_mirror, row_mirror) instead of ds_bpermute round trips; on top of the permlane-swap build
# speedup vs baseline: 1.0068x; 1.0068x over previous
; #define LAS __attribute__((address_space(3)))
; __device__ __forceinline__ unsigned pk2(float lo, float hi) { const f32x2_t v = {lo, hi}; return __builtin_bit_cast(unsigned, __builtin_convertvector(v, bf16x2_t)); }
; __device__ __forceinline__ f32x4 mfma16(bf16x8 a, bf16x8 b, f32x4 c) { return __builtin_amdgcn_mfma_f32_16x16x32_bf16(a, b, c, 0, 0, 0); }
; __device__ __forceinline__ void hgrn_build_vt(const LAS unsigned char* R, LAS unsigned char* VT, int i, int tq) {
;     unsigned raw[32];
; #pragma unroll
;     for (int uu = 0; uu < 32; ++uu) raw[uu] = *(const LAS unsigned short*)(R + (32 * tq + uu) * LSTR + 2 * i);
;     __builtin_amdgcn_sched_barrier(0);
; #pragma unroll
;     for (int m = 0; m < 4; ++m) { v4u w;
; #pragma unroll
;         for (int x = 0; x < 4; ++x) w[x] = raw[8 * m + 2 * x] | (raw[8 * m + 2 * x + 1] << 16);
;         *(LAS v4u*)(VT + i * LSTR + (32 * tq + 8 * m) * 2) = w; }
; }
; __device__ __forceinline__ void hgrn_pass2(const bf16* PROJ, const bf16* ST, const float* lbl, const float* gain, int e, bf16* MIX, int L, LAS unsigned char* lds) {
;     ...
;         { v4u cv[4]; hgrn_ld_chunks(pb + 1536, tid, cv); hgrn_st_chunks(SI, tid, cv); }
;         __syncthreads();
;         hgrn_build_vt(SI, VT, i, tq);
;         v4u gch[4];
; #pragma unroll
;         for (int m = 0; m < 4; ++m) { const int cc = lane + 64 * m; gch[m] = *(const v4u*)(pb + (size_t)(16 * I + (cc >> 4)) * EIN + 2048 + 8 * (cc & 15)); }
;         __syncthreads();
; #pragma unroll
;         for (int kp = 0; kp < 4; ++kp) {
;             v4u aw; aw.x = pk2(X[2 * kp][0], X[2 * kp][1]); aw.y = pk2(X[2 * kp][2], X[2 * kp][3]); aw.z = pk2(X[2 * kp + 1][0], X[2 * kp + 1][1]); aw.w = pk2(X[2 * kp + 1][2], X[2 * kp + 1][3]);
;             const bf16x8 af = as_bf8(aw);
; #pragma unroll
;             for (int dt = 0; dt < 8; ++dt) { const LAS unsigned char* vr = VT + (16 * dt + r16) * LSTR;
;                 const v2u lo = *(const LAS v2u*)(vr + (32 * kp + 4 * g4) * 2), hi = *(const LAS v2u*)(vr + (32 * kp + 16 + 4 * g4) * 2);
;                 v4u bw; bw.x = lo.x; bw.y = lo.y; bw.z = hi.x; bw.w = hi.y;
;                 O[dt] = mfma16(af, as_bf8(bw), O[dt]); }
.LBB0_270:
	s_waitcnt vmcnt(3)
	ds_write_b128 v162, v[232:235]
	s_waitcnt vmcnt(2)
	ds_write_b128 v163, v[236:239]
	s_waitcnt vmcnt(1)
	ds_write_b128 v164, v[240:243]
	s_waitcnt vmcnt(0)
	ds_write_b128 v165, v[252:255]
	s_waitcnt lgkmcnt(0)
	s_barrier
	ds_read_u16 v66, v152
	ds_read_u16 v67, v152 offset:272
	ds_read_u16 v68, v152 offset:544
	ds_read_u16 v69, v152 offset:816
	ds_read_u16 v70, v152 offset:1088
	ds_read_u16 v71, v152 offset:1360
	ds_read_u16 v72, v152 offset:1632
	ds_read_u16 v73, v152 offset:1904
	ds_read_u16 v74, v152 offset:2176
	ds_read_u16 v75, v152 offset:2448
	ds_read_u16 v76, v152 offset:2720
	ds_read_u16 v77, v152 offset:2992
	ds_read_u16 v78, v152 offset:3264
	ds_read_u16 v79, v152 offset:3536
	ds_read_u16 v80, v152 offset:3808
	ds_read_u16 v81, v152 offset:4080
	ds_read_u16 v82, v152 offset:4352
	ds_read_u16 v83, v152 offset:4624
	ds_read_u16 v84, v152 offset:4896
	ds_read_u16 v85, v152 offset:5168
	ds_read_u16 v122, v152 offset:5440
	ds_read_u16 v123, v152 offset:5712
	ds_read_u16 v124, v152 offset:5984
	ds_read_u16 v125, v152 offset:6256
	ds_read_u16 v126, v152 offset:6528
	ds_read_u16 v127, v152 offset:6800
	ds_read_u16 v128, v152 offset:7072
	ds_read_u16 v129, v152 offset:7344
	ds_read_u16 v130, v152 offset:7616
	ds_read_u16 v131, v152 offset:7888
	ds_read_u16 v162, v152 offset:8160
	ds_read_u16 v163, v152 offset:8432
	s_waitcnt lgkmcnt(14)
	v_lshl_or_b32 v66, v67, 16, v66
	v_lshl_or_b32 v67, v69, 16, v68
	v_lshl_or_b32 v68, v71, 16, v70
	v_lshl_or_b32 v69, v73, 16, v72
	ds_write_b128 v153, v[66:69]
	v_lshl_or_b32 v66, v75, 16, v74
	v_lshl_or_b32 v67, v77, 16, v76
	v_lshl_or_b32 v68, v79, 16, v78
	v_lshl_or_b32 v69, v81, 16, v80
	ds_write_b128 v153, v[66:69] offset:16
	v_lshl_or_b32 v66, v83, 16, v82
	s_waitcnt lgkmcnt(14)
	v_lshl_or_b32 v67, v85, 16, v84
	s_waitcnt lgkmcnt(12)
	v_lshl_or_b32 v68, v123, 16, v122
	s_waitcnt lgkmcnt(10)
	v_lshl_or_b32 v69, v125, 16, v124
	ds_write_b128 v153, v[66:69] offset:32
	s_waitcnt lgkmcnt(9)
	v_lshl_or_b32 v66, v127, 16, v126
	s_waitcnt lgkmcnt(7)
	v_lshl_or_b32 v67, v129, 16, v128
	s_waitcnt lgkmcnt(5)
	v_lshl_or_b32 v68, v131, 16, v130
	s_waitcnt lgkmcnt(3)
	v_lshl_or_b32 v69, v163, 16, v162
	ds_write_b128 v153, v[66:69] offset:48
	v_lshl_add_u64 v[66:67], s[36:37], 0, v[108:109]
	v_lshl_add_u64 v[66:67], v[66:67], 0, v[64:65]
	v_add_co_u32_e32 v66, vcc, s93, v66
	v_lshl_add_u64 v[68:69], s[36:37], 0, v[112:113]
	s_nop 0
	v_addc_co_u32_e32 v67, vcc, 0, v67, vcc
	v_lshl_add_u64 v[68:69], v[68:69], 0, v[64:65]
	v_add_co_u32_e32 v68, vcc, s93, v68
	v_cvt_pk_bf16_f32 v48, v48, v49
	s_nop 0
	v_addc_co_u32_e32 v69, vcc, 0, v69, vcc
	global_load_dwordx4 v[78:81], v[66:67], off
	global_load_dwordx4 v[74:77], v[68:69], off
	v_lshl_add_u64 v[66:67], s[36:37], 0, v[116:117]
	v_lshl_add_u64 v[66:67], v[66:67], 0, v[64:65]
	v_add_co_u32_e32 v66, vcc, s93, v66
	v_lshl_add_u64 v[68:69], s[36:37], 0, v[120:121]
	s_nop 0
	v_addc_co_u32_e32 v67, vcc, 0, v67, vcc
	v_lshl_add_u64 v[68:69], v[68:69], 0, v[64:65]
	v_add_co_u32_e32 v68, vcc, s93, v68
	v_cvt_pk_bf16_f32 v49, v50, v51
	s_nop 0
	v_addc_co_u32_e32 v69, vcc, 0, v69, vcc
	global_load_dwordx4 v[70:73], v[66:67], off
	s_nop 0
	global_load_dwordx4 v[66:69], v[68:69], off
	s_waitcnt lgkmcnt(0)
	s_barrier
	v_cvt_pk_bf16_f32 v50, v44, v45
	v_cvt_pk_bf16_f32 v51, v46, v47
	ds_read2_b64 v[44:47], v147 offset1:4
	v_add_u32_e32 v82, 0x1000, v147
	s_waitcnt lgkmcnt(0)
	v_mfma_f32_16x16x32_bf16 v[44:47], v[48:51], v[44:47], v[60:63]
	s_nop 2
	ds_read2_b64 v[60:63], v82 offset0:32 offset1:36
	v_add_u32_e32 v83, 0x2000, v147
	v_add_u32_e32 v84, 0x3000, v147
	s_waitcnt lgkmcnt(0)
	v_mfma_f32_16x16x32_bf16 v[56:59], v[48:51], v[60:63], v[56:59]
	ds_read2_b64 v[60:63], v83 offset0:64 offset1:68
	v_add_u32_e32 v85, 0x4000, v147
	v_add_u32_e32 v122, 0x5000, v147
	s_waitcnt lgkmcnt(0)
	v_mfma_f32_16x16x32_bf16 v[52:55], v[48:51], v[60:63], v[52:55]
	ds_read2_b64 v[60:63], v84 offset0:96 offset1:100
	v_add_u32_e32 v123, 0x6000, v147
	v_add_u32_e32 v124, 0x7000, v147
	s_waitcnt lgkmcnt(0)
	v_mfma_f32_16x16x32_bf16 v[40:43], v[48:51], v[60:63], v[40:43]
	ds_read2_b64 v[60:63], v85 offset0:128 offset1:132
	v_cvt_pk_bf16_f32 v20, v20, v21
	v_cvt_pk_bf16_f32 v21, v22, v23
	s_waitcnt lgkmcnt(0)
	v_mfma_f32_16x16x32_bf16 v[36:39], v[48:51], v[60:63], v[36:39]
	ds_read2_b64 v[60:63], v122 offset0:160 offset1:164
	v_cvt_pk_bf16_f32 v22, v16, v17
	v_cvt_pk_bf16_f32 v23, v18, v19
	s_waitcnt lgkmcnt(0)
	v_mfma_f32_16x16x32_bf16 v[32:35], v[48:51], v[60:63], v[32:35]
	ds_read2_b64 v[60:63], v123 offset0:192 offset1:196
	ds_read2_b64 v[16:19], v147 offset0:8 offset1:12
	v_cvt_pk_bf16_f32 v12, v12, v13
	s_waitcnt lgkmcnt(1)
	v_mfma_f32_16x16x32_bf16 v[28:31], v[48:51], v[60:63], v[28:31]
	ds_read2_b64 v[60:63], v124 offset0:224 offset1:228
	v_cvt_pk_bf16_f32 v13, v14, v15
	v_cvt_pk_bf16_f32 v14, v8, v9
	s_waitcnt lgkmcnt(0)
	v_mfma_f32_16x16x32_bf16 v[24:27], v[48:51], v[60:63], v[24:27]
	ds_read2_b64 v[48:51], v83 offset0:72 offset1:76
	v_cvt_pk_bf16_f32 v15, v10, v11
	ds_read2_b64 v[8:11], v147 offset0:16 offset1:20
	s_waitcnt lgkmcnt(1)
	v_mfma_f32_16x16x32_bf16 v[48:51], v[20:23], v[48:51], v[52:55]
	s_mov_b32 s2, 0x358637bd
	s_nop 1
	ds_read2_b64 v[52:55], v84 offset0:104 offset1:108
	s_brev_b32 s20, 60
	s_waitcnt lgkmcnt(0)
	v_mfma_f32_16x16x32_bf16 v[40:43], v[20:23], v[52:55], v[40:43]
	ds_read2_b64 v[52:55], v85 offset0:136 offset1:140
	s_lshl_b32 s90, s96, 2
	s_mov_b32 s86, 0x800000
	v_mfma_f32_16x16x32_bf16 v[16:19], v[20:23], v[16:19], v[44:47]
	s_nop 2
	ds_read2_b64 v[44:47], v82 offset0:40 offset1:44
	s_waitcnt lgkmcnt(1)
; #define LAS __attribute__((address_space(3)))
; __device__ __forceinline__ unsigned pk2(float lo, float hi) { const f32x2_t v = {lo, hi}; return __builtin_bit_cast(unsigned, __builtin_convertvector(v, bf16x2_t)); }
; __device__ __forceinline__ unsigned f2bf(float f) { return pk2(f, 0.f) & 0xffffu; }
; __device__ __forceinline__ f32x4 mfma16(bf16x8 a, bf16x8 b, f32x4 c) { return __builtin_amdgcn_mfma_f32_16x16x32_bf16(a, b, c, 0, 0, 0); }
; __device__ __forceinline__ void hgrn_pass2(const bf16* PROJ, const bf16* ST, const float* lbl, const float* gain, int e, bf16* MIX, int L, LAS unsigned char* lds) {
;     ...
;         for (int kp = 0; kp < 4; ++kp) {
;             v4u aw; aw.x = pk2(X[2 * kp][0], X[2 * kp][1]); aw.y = pk2(X[2 * kp][2], X[2 * kp][3]); aw.z = pk2(X[2 * kp + 1][0], X[2 * kp + 1][1]); aw.w = pk2(X[2 * kp + 1][2], X[2 * kp + 1][3]);
;             const bf16x8 af = as_bf8(aw);
; #pragma unroll
;             for (int dt = 0; dt < 8; ++dt) { const LAS unsigned char* vr = VT + (16 * dt + r16) * LSTR;
;                 const v2u lo = *(const LAS v2u*)(vr + (32 * kp + 4 * g4) * 2), hi = *(const LAS v2u*)(vr + (32 * kp + 16 + 4 * g4) * 2);
;                 v4u bw; bw.x = lo.x; bw.y = lo.y; bw.z = hi.x; bw.w = hi.y;
;                 O[dt] = mfma16(af, as_bf8(bw), O[dt]); }
;         }
; #pragma unroll
;         for (int r = 0; r < 4; ++r) { float ss = 0.f;
; #pragma unroll
;             for (int dt = 0; dt < 8; ++dt) ss += O[dt][r] * O[dt][r];
;             ss += __shfl_xor(ss, 1); ss += __shfl_xor(ss, 2); ss += __shfl_xor(ss, 4); ss += __shfl_xor(ss, 8);
;             const float rs = rsqrtf(ss * (1.0f / 128.0f) + 1e-6f);
; #pragma unroll
;             for (int dt = 0; dt < 8; ++dt) *(LAS unsigned short*)(BQ + (16 * I + 4 * g4 + r) * LSTR + (16 * dt + r16) * 2) = (unsigned short)f2bf(O[dt][r] * rs); }
	v_mfma_f32_16x16x32_bf16 v[36:39], v[20:23], v[52:55], v[36:39]
	ds_read2_b64 v[52:55], v122 offset0:168 offset1:172
	v_mfma_f32_16x16x32_bf16 v[8:11], v[12:15], v[8:11], v[16:19]
	s_nop 2
	ds_read2_b64 v[16:19], v82 offset0:48 offset1:52
	s_waitcnt lgkmcnt(2)
	v_mfma_f32_16x16x32_bf16 v[44:47], v[20:23], v[44:47], v[56:59]
	s_waitcnt lgkmcnt(1)
	v_mfma_f32_16x16x32_bf16 v[32:35], v[20:23], v[52:55], v[32:35]
	ds_read2_b64 v[52:55], v123 offset0:200 offset1:204
	s_waitcnt lgkmcnt(1)
	v_mfma_f32_16x16x32_bf16 v[16:19], v[12:15], v[16:19], v[44:47]
	s_nop 2
	ds_read2_b64 v[44:47], v84 offset0:112 offset1:116
	s_waitcnt lgkmcnt(1)
	v_mfma_f32_16x16x32_bf16 v[28:31], v[20:23], v[52:55], v[28:31]
	ds_read2_b64 v[52:55], v124 offset0:232 offset1:236
	s_waitcnt lgkmcnt(1)
	v_mfma_f32_16x16x32_bf16 v[40:43], v[12:15], v[44:47], v[40:43]
	ds_read2_b64 v[44:47], v85 offset0:144 offset1:148
	s_waitcnt lgkmcnt(1)
	v_mfma_f32_16x16x32_bf16 v[20:23], v[20:23], v[52:55], v[24:27]
	s_nop 2
	ds_read2_b64 v[24:27], v83 offset0:80 offset1:84
	s_waitcnt lgkmcnt(1)
	v_mfma_f32_16x16x32_bf16 v[36:39], v[12:15], v[44:47], v[36:39]
	ds_read2_b64 v[44:47], v122 offset0:176 offset1:180
	s_waitcnt lgkmcnt(1)
	v_mfma_f32_16x16x32_bf16 v[24:27], v[12:15], v[24:27], v[48:51]
	s_nop 2
	v_cvt_pk_bf16_f32 v48, v4, v5
	v_cvt_pk_bf16_f32 v49, v6, v7
	v_cvt_pk_bf16_f32 v50, v0, v1
	v_cvt_pk_bf16_f32 v51, v2, v3
	ds_read2_b64 v[0:3], v147 offset0:24 offset1:28
	s_waitcnt lgkmcnt(1)
	v_mfma_f32_16x16x32_bf16 v[32:35], v[12:15], v[44:47], v[32:35]
	ds_read2_b64 v[44:47], v123 offset0:208 offset1:212
	ds_read2_b64 v[4:7], v82 offset0:56 offset1:60
	s_waitcnt lgkmcnt(2)
	v_mfma_f32_16x16x32_bf16 v[0:3], v[48:51], v[0:3], v[8:11]
	s_nop 2
	ds_read2_b64 v[8:11], v83 offset0:88 offset1:92
	s_waitcnt lgkmcnt(2)
	v_mfma_f32_16x16x32_bf16 v[28:31], v[12:15], v[44:47], v[28:31]
	ds_read2_b64 v[44:47], v124 offset0:240 offset1:244
	s_waitcnt lgkmcnt(1)
	v_mfma_f32_16x16x32_bf16 v[8:11], v[48:51], v[8:11], v[24:27]
	s_nop 2
	ds_read2_b64 v[24:27], v123 offset0:216 offset1:220
	s_waitcnt lgkmcnt(1)
	v_mfma_f32_16x16x32_bf16 v[44:47], v[12:15], v[44:47], v[20:23]
	ds_read2_b64 v[12:15], v84 offset0:120 offset1:124
	v_mfma_f32_16x16x32_bf16 v[4:7], v[48:51], v[4:7], v[16:19]
	s_nop 0
	ds_read2_b64 v[20:23], v122 offset0:184 offset1:188
	s_nop 0
	ds_read2_b64 v[16:19], v85 offset0:152 offset1:156
	s_waitcnt lgkmcnt(3)
	v_mfma_f32_16x16x32_bf16 v[24:27], v[48:51], v[24:27], v[28:31]
	s_nop 2
	ds_read2_b64 v[28:31], v124 offset0:248 offset1:252
	s_waitcnt lgkmcnt(3)
	v_mfma_f32_16x16x32_bf16 v[12:15], v[48:51], v[12:15], v[40:43]
	s_waitcnt lgkmcnt(1)
	v_mfma_f32_16x16x32_bf16 v[16:19], v[48:51], v[16:19], v[36:39]
	s_nop 0
	v_mul_f32_e64 v40, v4, v4
	v_mul_f32_e64 v41, v5, v5
	v_pk_fma_f32 v[40:41], v[0:1], v[0:1], v[40:41]
	v_mfma_f32_16x16x32_bf16 v[20:23], v[48:51], v[20:23], v[32:35]
	v_mov_b32_e32 v38, v9
	v_mov_b32_e32 v39, v13
	v_pk_mul_f32 v[38:39], v[38:39], v[38:39]
	s_waitcnt lgkmcnt(0)
	v_mfma_f32_16x16x32_bf16 v[28:31], v[48:51], v[28:31], v[44:47]
	v_mov_b32_e32 v32, v8
	v_mov_b32_e32 v33, v12
	v_pk_mul_f32 v[32:33], v[32:33], v[32:33]
	v_mov_b32_e32 v34, v16
	v_mov_b32_e32 v35, v20
	v_mov_b32_e32 v42, v17
	v_mov_b32_e32 v43, v21
	v_mov_b32_e32 v46, v38
	v_mov_b32_e32 v47, v32
	v_pk_mul_f32 v[34:35], v[34:35], v[34:35]
	v_pk_mul_f32 v[42:43], v[42:43], v[42:43]
	v_pk_add_f32 v[40:41], v[40:41], v[46:47] op_sel:[1,0] op_sel_hi:[0,1]
	v_mov_b32_e32 v32, v39
	v_mov_b32_e32 v36, v24
	v_mov_b32_e32 v37, v28
	v_mov_b32_e32 v44, v25
	v_mov_b32_e32 v45, v29
	v_pk_add_f32 v[32:33], v[40:41], v[32:33]
	v_mov_b32_e32 v38, v42
	v_mov_b32_e32 v39, v34
	v_pk_mul_f32 v[36:37], v[36:37], v[36:37]
	v_pk_mul_f32 v[44:45], v[44:45], v[44:45]
	v_pk_add_f32 v[32:33], v[32:33], v[38:39]
	v_mov_b32_e32 v34, v43
	v_pk_add_f32 v[32:33], v[32:33], v[34:35]
	v_mov_b32_e32 v34, v44
	v_mov_b32_e32 v35, v36
	v_pk_add_f32 v[32:33], v[32:33], v[34:35]
	v_mov_b32_e32 v36, v45
	v_pk_add_f32 v[32:33], v[32:33], v[36:37]
	s_nop 1
	v_mov_b32_dpp v35, v33 quad_perm:[1,0,3,2] row_mask:0xf bank_mask:0xf
	v_mov_b32_dpp v34, v32 quad_perm:[1,0,3,2] row_mask:0xf bank_mask:0xf
	v_mov_b64_e32 v[40:41], s[2:3]
	s_mov_b32 s2, 0x800000
	v_mov_b32_e32 v37, v15
	v_mov_b32_e32 v38, v19
	s_waitcnt lgkmcnt(0)
	v_pk_add_f32 v[32:33], v[32:33], v[34:35]
	s_nop 1
	v_mov_b32_dpp v35, v33 quad_perm:[2,3,0,1] row_mask:0xf bank_mask:0xf
	v_mov_b32_dpp v34, v32 quad_perm:[2,3,0,1] row_mask:0xf bank_mask:0xf
	v_mov_b32_e32 v39, v23
	v_pk_mul_f32 v[38:39], v[38:39], v[38:39]
	v_mov_b32_e32 v42, v27
	v_mov_b32_e32 v43, v31
	s_waitcnt lgkmcnt(0)
	v_pk_add_f32 v[32:33], v[32:33], v[34:35]
	s_nop 1
	v_mov_b32_dpp v35, v33 row_half_mirror row_mask:0xf bank_mask:0xf
	v_mov_b32_dpp v34, v32 row_half_mirror row_mask:0xf bank_mask:0xf
	v_pk_mul_f32 v[42:43], v[42:43], v[42:43]
	v_readlane_b32 s3, v246, 1
	s_waitcnt lgkmcnt(0)
	v_pk_add_f32 v[32:33], v[32:33], v[34:35]
	s_nop 1
	v_mov_b32_dpp v35, v33 row_mirror row_mask:0xf bank_mask:0xf
	v_mov_b32_dpp v34, v32 row_mirror row_mask:0xf bank_mask:0xf
	s_waitcnt lgkmcnt(0)
; #define LAS __attribute__((address_space(3)))
; __device__ __forceinline__ unsigned f2bf(float f) { return pk2(f, 0.f) & 0xffffu; }
; __device__ __forceinline__ void hgrn_pass2(const bf16* PROJ, const bf16* ST, const float* lbl, const float* gain, int e, bf16* MIX, int L, LAS unsigned char* lds) {
;     ...
;         for (int r = 0; r < 4; ++r) { float ss = 0.f;
; #pragma unroll
;             for (int dt = 0; dt < 8; ++dt) ss += O[dt][r] * O[dt][r];
;             ss += __shfl_xor(ss, 1); ss += __shfl_xor(ss, 2); ss += __shfl_xor(ss, 4); ss += __shfl_xor(ss, 8);
;             const float rs = rsqrtf(ss * (1.0f / 128.0f) + 1e-6f);
; #pragma unroll
;             for (int dt = 0; dt < 8; ++dt) *(LAS unsigned short*)(BQ + (16 * I + 4 * g4 + r) * LSTR + (16 * dt + r16) * 2) = (unsigned short)f2bf(O[dt][r] * rs); }
; #pragma unroll
;         for (int m = 0; m < 4; ++m) { const int cc = lane + 64 * m, tl = cc >> 4, c8 = cc & 15;
;             const v4u ow = *(const LAS v4u*)(BQ + (16 * I + tl) * LSTR + c8 * 16);
;             const f32x4 ga = *(const f32x4*)(gain + 128 * h + 8 * c8), gb = *(const f32x4*)(gain + 128 * h + 8 * c8 + 4);
	v_pk_add_f32 v[32:33], v[32:33], v[34:35]
	s_nop 0
	v_pk_fma_f32 v[32:33], v[32:33], s[20:21], v[40:41] op_sel_hi:[1,0,0]
	s_nop 0
	v_mul_f32_e32 v34, 0x4b800000, v33
	v_cmp_gt_f32_e32 vcc, s2, v33
	s_nop 1
	v_cndmask_b32_e32 v33, v33, v34, vcc
	v_rsq_f32_e32 v33, v33
	v_pk_mul_f32 v[34:35], v[6:7], v[6:7]
	v_mul_f32_e32 v36, 0x45800000, v33
	v_cndmask_b32_e32 v33, v33, v36, vcc
	v_mul_f32_e32 v0, v0, v33
	v_cvt_pk_bf16_f32 v0, v0, s0
	ds_write_b16 v154, v0
	v_mul_f32_e32 v0, v4, v33
	v_cvt_pk_bf16_f32 v0, v0, s0
	ds_write_b16 v154, v0 offset:32
	v_mul_f32_e32 v0, v8, v33
	v_cvt_pk_bf16_f32 v0, v0, s0
	ds_write_b16 v154, v0 offset:64
	v_mul_f32_e32 v0, v12, v33
	v_cvt_pk_bf16_f32 v0, v0, s0
	ds_write_b16 v154, v0 offset:96
	v_mul_f32_e32 v0, v16, v33
	v_cvt_pk_bf16_f32 v0, v0, s0
	ds_write_b16 v154, v0 offset:128
	v_mul_f32_e32 v0, v20, v33
	v_cvt_pk_bf16_f32 v0, v0, s0
	ds_write_b16 v154, v0 offset:160
	v_mul_f32_e32 v0, v24, v33
	v_cvt_pk_bf16_f32 v0, v0, s0
	ds_write_b16 v154, v0 offset:192
	v_mul_f32_e32 v0, 0x4b800000, v32
	v_cmp_gt_f32_e32 vcc, s2, v32
	v_mul_f32_e32 v4, v28, v33
	v_cvt_pk_bf16_f32 v4, v4, s0
	v_cndmask_b32_e32 v0, v32, v0, vcc
	v_rsq_f32_e32 v0, v0
	ds_write_b16 v154, v4 offset:224
	v_mov_b32_e32 v36, v11
	v_pk_mul_f32 v[36:37], v[36:37], v[36:37]
	v_mul_f32_e32 v4, 0x45800000, v0
	v_cndmask_b32_e32 v12, v0, v4, vcc
	v_mul_f32_e32 v0, v1, v12
	v_cvt_pk_bf16_f32 v0, v0, s0
	ds_write_b16 v154, v0 offset:272
	v_mul_f32_e32 v0, v5, v12
	v_cvt_pk_bf16_f32 v8, v0, s0
	v_mov_b32_e32 v0, v10
	v_mov_b32_e32 v1, v14
	v_pk_mul_f32 v[0:1], v[0:1], v[0:1]
	v_pk_fma_f32 v[34:35], v[2:3], v[2:3], v[34:35]
	v_mov_b32_e32 v4, v18
	v_mov_b32_e32 v5, v22
	v_mov_b32_e32 v44, v36
	v_mov_b32_e32 v45, v0
	v_pk_mul_f32 v[4:5], v[4:5], v[4:5]
	v_pk_add_f32 v[34:35], v[34:35], v[44:45] op_sel:[1,0] op_sel_hi:[0,1]
	v_mov_b32_e32 v0, v37
	v_mov_b32_e32 v32, v26
	v_mov_b32_e32 v33, v30
	v_pk_add_f32 v[0:1], v[34:35], v[0:1]
	v_mov_b32_e32 v34, v38
	v_mov_b32_e32 v35, v4
	v_pk_mul_f32 v[32:33], v[32:33], v[32:33]
	v_pk_add_f32 v[0:1], v[0:1], v[34:35]
	v_mov_b32_e32 v4, v39
	v_pk_add_f32 v[0:1], v[0:1], v[4:5]
	v_mov_b32_e32 v4, v42
	v_mov_b32_e32 v5, v32
	v_pk_add_f32 v[0:1], v[0:1], v[4:5]
	v_mov_b32_e32 v32, v43
	v_pk_add_f32 v[0:1], v[0:1], v[32:33]
	s_nop 1
	v_mov_b32_dpp v5, v1 quad_perm:[1,0,3,2] row_mask:0xf bank_mask:0xf
	v_mov_b32_dpp v4, v0 quad_perm:[1,0,3,2] row_mask:0xf bank_mask:0xf
	ds_write_b16 v154, v8 offset:304
	v_mul_f32_e32 v8, v9, v12
	v_cvt_pk_bf16_f32 v8, v8, s0
	ds_write_b16 v154, v8 offset:336
	s_waitcnt lgkmcnt(2)
	v_pk_add_f32 v[0:1], v[0:1], v[4:5]
	s_nop 1
	v_mov_b32_dpp v5, v1 quad_perm:[2,3,0,1] row_mask:0xf bank_mask:0xf
	v_mov_b32_dpp v4, v0 quad_perm:[2,3,0,1] row_mask:0xf bank_mask:0xf
	v_mul_f32_e32 v8, v13, v12
	v_cvt_pk_bf16_f32 v8, v8, s0
	ds_write_b16 v154, v8 offset:368
	v_mul_f32_e32 v8, v17, v12
	s_waitcnt lgkmcnt(1)
	v_pk_add_f32 v[0:1], v[0:1], v[4:5]
	s_nop 1
	v_mov_b32_dpp v5, v1 row_half_mirror row_mask:0xf bank_mask:0xf
	v_mov_b32_dpp v4, v0 row_half_mirror row_mask:0xf bank_mask:0xf
	v_cvt_pk_bf16_f32 v8, v8, s0
	ds_write_b16 v154, v8 offset:400
	v_mul_f32_e32 v8, v21, v12
	v_cvt_pk_bf16_f32 v13, v8, s0
	s_waitcnt lgkmcnt(1)
	v_pk_add_f32 v[4:5], v[0:1], v[4:5]
	v_lshl_add_u64 v[0:1], v[86:87], 0, s[90:91]
	global_load_dwordx4 v[32:35], v[0:1], off offset:16
	global_load_dwordx4 v[36:39], v[0:1], off
	s_nop 1
	v_mov_b32_dpp v9, v5 row_mirror row_mask:0xf bank_mask:0xf
	v_mov_b32_dpp v8, v4 row_mirror row_mask:0xf bank_mask:0xf
	ds_write_b16 v154, v13 offset:432
	v_mul_f32_e32 v13, v25, v12
	v_cvt_pk_bf16_f32 v13, v13, s0
	ds_write_b16 v154, v13 offset:464
	s_waitcnt lgkmcnt(2)
	v_pk_add_f32 v[4:5], v[4:5], v[8:9]
	s_waitcnt vmcnt(5)
	v_and_b32_e32 v13, 0xffff0000, v78
	v_pk_fma_f32 v[4:5], v[4:5], s[20:21], v[40:41] op_sel_hi:[1,0,0]
	s_waitcnt vmcnt(4)
	v_lshlrev_b32_e32 v16, 16, v74
	v_mul_f32_e32 v8, 0x4b800000, v5
	v_cmp_gt_f32_e32 vcc, s2, v5
	v_and_b32_e32 v17, 0xffff0000, v74
	s_waitcnt vmcnt(3)
	v_lshlrev_b32_e32 v20, 16, v70
	v_cndmask_b32_e32 v5, v5, v8, vcc
	v_rsq_f32_e32 v5, v5
	v_mul_f32_e32 v8, v29, v12
	v_cvt_pk_bf16_f32 v8, v8, s0
	ds_write_b16 v154, v8 offset:496
	v_mul_f32_e32 v8, 0x45800000, v5
	v_cndmask_b32_e32 v5, v5, v8, vcc
	v_mul_f32_e32 v2, v2, v5
	v_cvt_pk_bf16_f32 v2, v2, s0
	ds_write_b16 v154, v2 offset:544
	v_mul_f32_e32 v2, v6, v5
	v_cvt_pk_bf16_f32 v2, v2, s0
	ds_write_b16 v154, v2 offset:576
	v_mul_f32_e32 v2, v10, v5
	v_cvt_pk_bf16_f32 v2, v2, s0
	ds_write_b16 v154, v2 offset:608
	v_mul_f32_e32 v2, v14, v5
	v_cvt_pk_bf16_f32 v2, v2, s0
	ds_write_b16 v154, v2 offset:640
	v_mul_f32_e32 v2, v18, v5
	v_cvt_pk_bf16_f32 v2, v2, s0
	ds_write_b16 v154, v2 offset:672
	v_mul_f32_e32 v2, v22, v5
	v_cvt_pk_bf16_f32 v2, v2, s0
	ds_write_b16 v154, v2 offset:704
	v_mul_f32_e32 v2, v26, v5
	v_cvt_pk_bf16_f32 v2, v2, s0
	ds_write_b16 v154, v2 offset:736
	v_mul_f32_e32 v2, 0x4b800000, v4
	v_cmp_gt_f32_e32 vcc, s2, v4
	v_lshlrev_b32_e32 v12, 16, v78
	s_add_u32 s2, s66, s27
	v_cndmask_b32_e32 v2, v4, v2, vcc
	v_rsq_f32_e32 v2, v2
	v_mul_f32_e32 v4, v30, v5
	v_cvt_pk_bf16_f32 v4, v4, s0
	ds_write_b16 v154, v4 offset:768
	v_mul_f32_e32 v4, 0x45800000, v2
	v_cndmask_b32_e32 v2, v2, v4, vcc
	v_mul_f32_e32 v3, v3, v2
	v_cvt_pk_bf16_f32 v3, v3, s0
	ds_write_b16 v154, v3 offset:816
	v_mul_f32_e32 v3, v7, v2
	v_cvt_pk_bf16_f32 v3, v3, s0
	ds_write_b16 v154, v3 offset:848
	v_mul_f32_e32 v3, v11, v2
	v_cvt_pk_bf16_f32 v3, v3, s0
	ds_write_b16 v154, v3 offset:880
	v_mul_f32_e32 v3, v15, v2
	v_cvt_pk_bf16_f32 v3, v3, s0
	ds_write_b16 v154, v3 offset:912
	v_mul_f32_e32 v3, v19, v2
	v_cvt_pk_bf16_f32 v3, v3, s0
	ds_write_b16 v154, v3 offset:944
	v_mul_f32_e32 v3, v23, v2
	v_cvt_pk_bf16_f32 v3, v3, s0
	ds_write_b16 v154, v3 offset:976
	v_mul_f32_e32 v3, v27, v2
	v_mul_f32_e32 v2, v31, v2
	v_cvt_pk_bf16_f32 v3, v3, s0
	v_cvt_pk_bf16_f32 v2, v2, s0
	ds_write_b16 v154, v3 offset:1008
	ds_write_b16 v154, v2 offset:1040
	ds_read_b128 v[4:7], v155
	ds_read_b128 v[8:11], v156
	s_addc_u32 s3, s67, s3
	s_lshl_b32 s90, s96, 1
	v_lshl_add_u64 v[2:3], v[88:89], 0, s[90:91]
	s_waitcnt lgkmcnt(1)
; #define LAS __attribute__((address_space(3)))
; __device__ __forceinline__ unsigned pk2(float lo, float hi) { const f32x2_t v = {lo, hi}; return __builtin_bit_cast(unsigned, __builtin_convertvector(v, bf16x2_t)); }
; __device__ __forceinline__ void hgrn_pass2(const bf16* PROJ, const bf16* ST, const float* lbl, const float* gain, int e, bf16* MIX, int L, LAS unsigned char* lds) {
;     ...
; #pragma unroll
;         for (int m = 0; m < 4; ++m) { const int cc = lane + 64 * m, tl = cc >> 4, c8 = cc & 15;
;             const v4u ow = *(const LAS v4u*)(BQ + (16 * I + tl) * LSTR + c8 * 16);
;             const f32x4 ga = *(const f32x4*)(gain + 128 * h + 8 * c8), gb = *(const f32x4*)(gain + 128 * h + 8 * c8 + 4);
;             v4u yw;
; #pragma unroll
;             for (int x = 0; x < 4; ++x) { const float g0 = bflo(gch[m][x]), g1 = bfhi(gch[m][x]);
;                 const float y0 = bflo(ow[x]) * (x < 2 ? ga[2 * x] : gb[2 * x - 4]) * g0;
;                 const float y1 = bfhi(ow[x]) * (x < 2 ? ga[2 * x + 1] : gb[2 * x - 3]) * g1;
;                 yw[x] = pk2(y0, y1); }
;             *(v4u*)(MIX + (rowseg + 16 * I + tl) * D + 128 * h + 8 * c8) = yw; }
	v_lshlrev_b32_e32 v14, 16, v4
	v_and_b32_e32 v15, 0xffff0000, v4
	s_waitcnt vmcnt(0)
	v_pk_mul_f32 v[14:15], v[36:37], v[14:15]
	s_waitcnt lgkmcnt(0)
	v_lshlrev_b32_e32 v18, 16, v8
	v_pk_mul_f32 v[12:13], v[14:15], v[12:13]
	v_lshlrev_b32_e32 v14, 16, v5
	v_and_b32_e32 v15, 0xffff0000, v5
	v_cvt_pk_bf16_f32 v4, v12, v13
	v_lshlrev_b32_e32 v12, 16, v79
	v_and_b32_e32 v13, 0xffff0000, v79
	v_pk_mul_f32 v[14:15], v[38:39], v[14:15]
	v_and_b32_e32 v19, 0xffff0000, v8
	v_pk_mul_f32 v[12:13], v[14:15], v[12:13]
	v_lshlrev_b32_e32 v14, 16, v6
	v_and_b32_e32 v15, 0xffff0000, v6
	v_cvt_pk_bf16_f32 v5, v12, v13
	v_lshlrev_b32_e32 v12, 16, v80
	v_and_b32_e32 v13, 0xffff0000, v80
	v_pk_mul_f32 v[14:15], v[32:33], v[14:15]
	v_lshlrev_b32_e32 v8, 16, v9
	v_pk_mul_f32 v[12:13], v[14:15], v[12:13]
	v_lshlrev_b32_e32 v14, 16, v7
	v_and_b32_e32 v15, 0xffff0000, v7
	v_cvt_pk_bf16_f32 v6, v12, v13
	v_lshlrev_b32_e32 v12, 16, v81
	v_and_b32_e32 v13, 0xffff0000, v81
	v_pk_mul_f32 v[14:15], v[34:35], v[14:15]
	v_and_b32_e32 v9, 0xffff0000, v9
	v_pk_mul_f32 v[12:13], v[14:15], v[12:13]
	v_and_b32_e32 v21, 0xffff0000, v70
	v_cvt_pk_bf16_f32 v7, v12, v13
	v_mov_b32_e32 v13, s3
	v_or_b32_e32 v12, s2, v90
	v_lshlrev_b64 v[12:13], 11, v[12:13]
	v_lshl_add_u64 v[12:13], v[2:3], 0, v[12:13]
	global_store_dwordx4 v[12:13], v[4:7], off
	s_nop 1
	v_mov_b32_e32 v4, v36
	v_mov_b32_e32 v5, v37
	v_mov_b32_e32 v6, v38
	v_mov_b32_e32 v7, v39
	v_mov_b32_e32 v12, v32
	v_mov_b32_e32 v13, v33
	v_mov_b32_e32 v14, v34
	v_mov_b32_e32 v15, v35
	v_pk_mul_f32 v[4:5], v[4:5], v[18:19]
	s_nop 0
	v_pk_mul_f32 v[4:5], v[4:5], v[16:17]
	v_lshlrev_b32_e32 v16, 16, v75
	v_and_b32_e32 v17, 0xffff0000, v75
	v_pk_mul_f32 v[6:7], v[6:7], v[8:9]
	v_lshlrev_b32_e32 v8, 16, v10
	v_pk_mul_f32 v[6:7], v[6:7], v[16:17]
	v_and_b32_e32 v9, 0xffff0000, v10
	v_cvt_pk_bf16_f32 v4, v4, v5
	v_cvt_pk_bf16_f32 v5, v6, v7
	v_lshlrev_b32_e32 v6, 16, v76
	v_and_b32_e32 v7, 0xffff0000, v76
	v_pk_mul_f32 v[8:9], v[12:13], v[8:9]
	v_lshlrev_b32_e32 v10, 16, v11
	v_and_b32_e32 v11, 0xffff0000, v11
	v_pk_mul_f32 v[6:7], v[8:9], v[6:7]
	v_lshlrev_b32_e32 v8, 16, v77
	v_and_b32_e32 v9, 0xffff0000, v77
	v_pk_mul_f32 v[10:11], v[14:15], v[10:11]
	v_cvt_pk_bf16_f32 v6, v6, v7
	v_pk_mul_f32 v[8:9], v[10:11], v[8:9]
	s_nop 0
	v_cvt_pk_bf16_f32 v7, v8, v9
	v_mov_b32_e32 v9, s3
	v_or_b32_e32 v8, s2, v110
	v_lshlrev_b64 v[8:9], 11, v[8:9]
	v_lshl_add_u64 v[8:9], v[2:3], 0, v[8:9]
	global_store_dwordx4 v[8:9], v[4:7], off
	s_nop 1
	v_mov_b32_e32 v4, v36
	v_mov_b32_e32 v5, v37
	v_mov_b32_e32 v6, v38
	v_mov_b32_e32 v7, v39
	v_mov_b32_e32 v8, v32
	v_mov_b32_e32 v9, v33
	v_mov_b32_e32 v10, v34
	v_mov_b32_e32 v11, v35
	ds_read_b128 v[12:15], v157
	ds_read_b128 v[16:19], v158
	s_waitcnt lgkmcnt(1)
	v_lshlrev_b32_e32 v22, 16, v12
	v_and_b32_e32 v23, 0xffff0000, v12
	v_lshlrev_b32_e32 v12, 16, v13
	v_and_b32_e32 v13, 0xffff0000, v13
	v_pk_mul_f32 v[4:5], v[4:5], v[22:23]
	s_nop 0
	v_pk_mul_f32 v[4:5], v[4:5], v[20:21]
	v_lshlrev_b32_e32 v20, 16, v71
	v_and_b32_e32 v21, 0xffff0000, v71
	v_pk_mul_f32 v[6:7], v[6:7], v[12:13]
	v_lshlrev_b32_e32 v12, 16, v14
	v_pk_mul_f32 v[6:7], v[6:7], v[20:21]
	v_and_b32_e32 v13, 0xffff0000, v14
	v_cvt_pk_bf16_f32 v4, v4, v5
	v_cvt_pk_bf16_f32 v5, v6, v7
	v_lshlrev_b32_e32 v6, 16, v72
	v_and_b32_e32 v7, 0xffff0000, v72
	v_pk_mul_f32 v[8:9], v[8:9], v[12:13]
	v_lshlrev_b32_e32 v12, 16, v15
	v_and_b32_e32 v13, 0xffff0000, v15
	v_pk_mul_f32 v[6:7], v[8:9], v[6:7]
	v_lshlrev_b32_e32 v8, 16, v73
	v_and_b32_e32 v9, 0xffff0000, v73
	v_pk_mul_f32 v[10:11], v[10:11], v[12:13]
	v_cvt_pk_bf16_f32 v6, v6, v7
	v_pk_mul_f32 v[8:9], v[10:11], v[8:9]
	s_waitcnt lgkmcnt(0)
	v_lshlrev_b32_e32 v12, 16, v16
	v_cvt_pk_bf16_f32 v7, v8, v9
	v_mov_b32_e32 v9, s3
	v_or_b32_e32 v8, s2, v114
	v_lshlrev_b64 v[8:9], 11, v[8:9]
	v_lshl_add_u64 v[8:9], v[2:3], 0, v[8:9]
	global_store_dwordx4 v[8:9], v[4:7], off
	s_nop 1
	v_mov_b32_e32 v4, v36
	v_mov_b32_e32 v5, v37
	v_mov_b32_e32 v6, v38
	v_mov_b32_e32 v7, v39
	v_mov_b32_e32 v8, v32
	v_mov_b32_e32 v9, v33
	v_mov_b32_e32 v10, v34
	v_mov_b32_e32 v11, v35
	v_and_b32_e32 v13, 0xffff0000, v16
	v_lshlrev_b32_e32 v0, 16, v66
	v_and_b32_e32 v1, 0xffff0000, v66
	v_pk_mul_f32 v[4:5], v[4:5], v[12:13]
	s_nop 0
	v_pk_mul_f32 v[0:1], v[4:5], v[0:1]
	v_lshlrev_b32_e32 v12, 16, v17
	v_and_b32_e32 v13, 0xffff0000, v17
	v_cvt_pk_bf16_f32 v4, v0, v1
	v_lshlrev_b32_e32 v0, 16, v67
	v_and_b32_e32 v1, 0xffff0000, v67
	v_pk_mul_f32 v[6:7], v[6:7], v[12:13]
	s_nop 0
	v_pk_mul_f32 v[0:1], v[6:7], v[0:1]
	v_lshlrev_b32_e32 v6, 16, v18
	v_and_b32_e32 v7, 0xffff0000, v18
	v_cvt_pk_bf16_f32 v5, v0, v1
	v_lshlrev_b32_e32 v0, 16, v68
	v_and_b32_e32 v1, 0xffff0000, v68
	v_pk_mul_f32 v[6:7], v[8:9], v[6:7]
	v_lshlrev_b32_e32 v8, 16, v19
	v_pk_mul_f32 v[0:1], v[6:7], v[0:1]
	v_and_b32_e32 v9, 0xffff0000, v19
	v_cvt_pk_bf16_f32 v6, v0, v1
	v_lshlrev_b32_e32 v0, 16, v69
	v_and_b32_e32 v1, 0xffff0000, v69
	v_pk_mul_f32 v[8:9], v[10:11], v[8:9]
	s_nop 0
	v_pk_mul_f32 v[0:1], v[8:9], v[0:1]
	s_nop 0
	v_cvt_pk_bf16_f32 v7, v0, v1
	v_mov_b32_e32 v1, s3
	v_or_b32_e32 v0, s2, v118
	v_readlane_b32 s2, v247, 18
	v_lshlrev_b64 v[0:1], 11, v[0:1]
	s_add_i32 s26, s26, s2
	v_readlane_b32 s2, v247, 61
	v_lshl_add_u64 v[0:1], v[2:3], 0, v[0:1]
	s_cmp_ge_i32 s26, s2
	v_readlane_b32 s3, v247, 19
	global_store_dwordx4 v[0:1], v[4:7], off
	s_cbranch_scc1 .LBB0_266
